# poolsplit
# speedup vs baseline: 1.0294x; 1.0160x over previous
; __device__ __forceinline__ void attn_passes(const Params& p, LAS unsigned char* lds) {
;     ...
;     const int nk = ((int)blockIdx.x < 256) ? (256 - (int)blockIdx.x + G - 1) / G : 0, nunits = 6 * nk;
; __device__ __forceinline__ void p3_pool(const Params& p) {
;     const bf16_t* proj = (const bf16_t*)(p.ws + WS_PROJ2); bf16_t* ycat = (bf16_t*)(p.ws + WS_YCAT);
;     const int tid = threadIdx.x, cch = tid & 255, sub = tid >> 8, j0 = cch * 8;
;     const int w = 2 << (j0 >> 9);
;     float ps[8];
;     { const f32x4 a = *(const f32x4*)(p.pool_scale + j0), b = *(const f32x4*)(p.pool_scale + j0 + 4); ps[0] = a[0]; ps[1] = a[1]; ps[2] = a[2]; ps[3] = a[3]; ps[4] = b[0]; ps[5] = b[1]; ps[6] = b[2]; ps[7] = b[3]; }
;     for (int item = blockIdx.x; item < 256; item += gridDim.x) {
;         const int t0 = item * 64 + sub * 32, pos0 = t0 & (SEQ - 1);
.LBB0_248:
	s_cmp_lt_i32 s37, 1
	s_cbranch_scc1 .LBB0_316
	s_bitcmp1_b32 s2, 0
	s_cbranch_scc0 .Lpq_skip
	v_writelane_b32 v238, s4, 0
	v_writelane_b32 v238, s5, 1
	v_writelane_b32 v238, s6, 2
	v_writelane_b32 v238, s7, 3
	v_writelane_b32 v238, s8, 4
	v_writelane_b32 v238, s9, 5
	v_writelane_b32 v238, s10, 6
	v_writelane_b32 v238, s11, 7
	v_writelane_b32 v238, s12, 8
	v_writelane_b32 v238, s13, 9
	v_writelane_b32 v238, s22, 10
	v_writelane_b32 v238, s23, 11
	v_and_b32_e32 v34, 0x7f8, v172
	v_lshlrev_b32_e32 v8, 2, v34
	global_load_dwordx4 v[0:3], v8, s[30:31]
	global_load_dwordx4 v[4:7], v8, s[30:31] offset:16
	v_lshrrev_b32_e32 v24, 9, v34
	v_lshlrev_b32_e32 v16, 1, v34
	v_readfirstlane_b32 s100, v24
	v_readfirstlane_b32 s96, v173
	v_add_u32_e32 v17, 0x2000, v16
	v_add_u32_e32 v16, 0x1000, v16
	v_sub_u32_e32 v19, 126, v24
	v_lshlrev_b32_e32 v19, 23, v19
	s_nop 3
	s_lshl_b32 s100, 2, s100
	s_add_i32 s11, s100, -1
	s_mul_i32 s22, s11, 0x3000
	s_mov_b32 s12, s2
	s_waitcnt vmcnt(0)

; #define LAS __attribute__((address_space(3)))
; __device__ __forceinline__ void unpack8(const u32x4 w, float (&f)[8]) { f[0] = bf_lo(w.x); f[1] = bf_hi(w.x); f[2] = bf_lo(w.y); f[3] = bf_hi(w.y); f[4] = bf_lo(w.z); f[5] = bf_hi(w.z); f[6] = bf_lo(w.w); f[7] = bf_hi(w.w); }
; __device__ __forceinline__ void attn_passes(const Params& p, LAS unsigned char* lds) {
;     ...
;     const int tid = threadIdx.x, w = __builtin_amdgcn_readfirstlane(tid >> 6), lane = tid & 63, qi = lane & 15, g = lane >> 4;
;     const int G = gridDim.x;
;     const float sc2 = 0.08838834764831845f * 1.4426950408889634f;
;     const int srow = tid >> 4, spc = tid & 15;
;     const int sch = spc ^ (((srow & 3) << 2) | ((srow >> 2) & 3));
;     const int krow = 8 * (qi >> 2) + (qi & 3);
;     unsigned koff[8], qrd[4];
; #pragma unroll
;     for (int ks = 0; ks < 4; ++ks) { koff[ks] = v_off(krow, 4 * ks + g); koff[4 + ks] = v_off(krow + 4, 4 * ks + g); qrd[ks] = QBUF_OFF + v_off(16 * w + qi, 4 * ks + g); }
;     unsigned tra[2];
;     { const int q4 = (lane & 15) >> 2, p4 = lane & 3;
; #pragma unroll
;       for (int t = 0; t < 2; ++t) tra[t] = v_off(8 * g + 4 * t + q4, p4 >> 1) + 8u * (p4 & 1); }
;     LAS unsigned char* ldsw = lds + w * 1024;
; __device__ __forceinline__ void p3_pool(const Params& p) {
;     ...
;             if (pos - (w - 1) >= 0) { float f[8]; unpack8(*(const u32x4*)(proj + (size_t)(t - (w - 1)) * NP2 + P2_U + j0), f);
; #pragma unroll
;                 for (int j = 0; j < 8; ++j) sum[j] -= f[j]; }
;         }
;     }
.Lpq_nolag_8:
	s_add_i32 s23, s23, 1
	s_add_i32 s13, s13, 1
	s_cmp_lt_u32 s13, 4
	s_cbranch_scc1 .Lpq_pair
	s_add_i32 s12, s12, s34
	s_cmpk_gt_i32 s12, 0xff
	s_cbranch_scc0 .Lpq_item
	v_and_b32_e32 v34, 0x7f8, v172
	v_mov_b32_e32 v9, 0
	v_readlane_b32 s4, v238, 0
	v_readlane_b32 s5, v238, 1
	v_readlane_b32 s6, v238, 2
	v_readlane_b32 s7, v238, 3
	v_readlane_b32 s8, v238, 4
	v_readlane_b32 s9, v238, 5
	v_readlane_b32 s10, v238, 6
	v_readlane_b32 s11, v238, 7
	v_readlane_b32 s12, v238, 8
	v_readlane_b32 s13, v238, 9
	v_readlane_b32 s22, v238, 10
	v_readlane_b32 s23, v238, 11
	s_nop 4
.Lpq_skip:
	v_lshrrev_b32_e32 v131, 4, v128
	v_lshlrev_b32_e32 v3, 2, v131
	v_and_b32_e32 v0, 12, v3
	v_bfe_u32 v1, v128, 6, 2
	s_lshr_b32 s9, s8, 6
	v_bitop3_b32 v0, v0, v171, v1 bitop3:0x36
	s_lshl_b32 s4, s9, 10
	v_lshlrev_b32_e32 v90, 4, v0
	v_mov_b32_e32 v91, 0
	s_add_i32 s55, s4, 0
	v_lshl_add_u64 v[0:1], s[42:43], 0, v[90:91]
	s_mov_b64 s[4:5], 0x15600000
	v_bfe_u32 v2, v128, 4, 2
	v_lshrrev_b32_e32 v4, 2, v171
	v_and_b32_e32 v5, 3, v128
	v_lshrrev_b32_e32 v8, 1, v171
	v_lshl_add_u64 v[94:95], v[0:1], 0, s[4:5]
	s_mov_b64 s[4:5], 0x19600000
	v_lshl_or_b32 v5, v4, 3, v5
	v_and_b32_e32 v7, 12, v130
	v_and_b32_e32 v8, 2, v8
	v_or_b32_e32 v12, 4, v2
	v_lshl_add_u64 v[96:97], v[0:1], 0, s[4:5]
	v_cvt_f32_u32_e32 v1, s37
	v_lshlrev_b32_e32 v6, 8, v5
	v_bitop3_b32 v13, v8, v12, v7 bitop3:0x36
	v_lshl_or_b32 v139, v13, 4, v6
	v_or_b32_e32 v13, 8, v2
	v_bitop3_b32 v14, v8, v13, v7 bitop3:0x36
	v_or_b32_e32 v5, 4, v5
	v_lshl_or_b32 v174, v14, 4, v6
	v_or_b32_e32 v14, 12, v2
	v_rcp_iflag_f32_e32 v1, v1
	v_lshlrev_b32_e32 v9, 8, v5
	v_bfe_u32 v5, v5, 2, 2
	v_bitop3_b32 v11, v8, v2, v7 bitop3:0x36
	v_bitop3_b32 v8, v8, v14, v7 bitop3:0x36
	v_or_b32_e32 v10, v7, v152
	v_lshl_or_b32 v135, v11, 4, v6
	v_bitop3_b32 v11, v5, v2, v7 bitop3:0x36
	v_bitop3_b32 v12, v5, v12, v7 bitop3:0x36
	v_bitop3_b32 v13, v5, v13, v7 bitop3:0x36
	v_lshl_or_b32 v176, v8, 4, v6
	v_bitop3_b32 v5, v5, v14, v7 bitop3:0x36
	v_lshlrev_b32_e32 v6, 3, v2
	v_lshl_or_b32 v137, v11, 4, v9
	v_bitop3_b32 v11, v7, v2, v152 bitop3:0x36
	v_lshl_or_b32 v141, v12, 4, v9
	v_bitop3_b32 v12, v2, v10, 4 bitop3:0x36
	v_lshl_or_b32 v175, v13, 4, v9
	v_bitop3_b32 v13, v2, v10, 8 bitop3:0x36
	v_lshl_or_b32 v177, v5, 4, v9
	v_bitop3_b32 v5, v2, v10, 12 bitop3:0x36
	v_bfe_u32 v7, v128, 1, 1
	v_and_b32_e32 v8, 12, v128
	v_or_b32_e32 v10, v6, v4
	v_and_b32_e32 v14, 2, v133
	s_mul_i32 s54, s37, 6
	s_lshl_b32 s10, s9, 12
	v_lshlrev_b32_e32 v10, 8, v10
	v_or3_b32 v14, v8, v14, v7
	v_mul_f32_e32 v1, 0x4f7ffffe, v1
	v_lshl_or_b32 v10, v14, 4, v10
	v_or_b32_e32 v14, 4, v6
	v_lshl_add_u64 v[92:93], s[6:7], 0, v[90:91]
	s_add_i32 s56, s55, 0x20000
	s_lshr_b32 s6, s8, 7
	s_max_i32 s57, s54, 1
	s_add_i32 s58, s55, 0x10000
	s_add_i32 s59, s55, 0x12000
	s_add_i32 s60, s55, 0x14000
	s_add_i32 s61, s55, 0x16000
	s_add_i32 s62, s55, 0x18000
	s_add_i32 s63, s55, 0x1a000
	s_add_i32 s64, s55, 0x1c000
	s_add_i32 s65, s55, 0x1e000
	s_add_i32 s66, s55, 0x22000
	s_add_i32 s67, s55, 0x24000
	s_add_i32 s68, s55, 0x26000
	s_add_i32 s10, s10, 0
	v_cvt_u32_f32_e32 v1, v1
	v_or_b32_e32 v4, v14, v4
	v_bfe_u32 v14, v14, 2, 2
	s_add_u32 s69, s42, 0x3d600000
	v_lshlrev_b32_e32 v4, 8, v4
	v_bitop3_b32 v7, v14, v7, v8 bitop3:0x36
	s_addc_u32 s70, s43, 0
	v_and_b32_e32 v9, 8, v172
	v_lshl_or_b32 v4, v7, 4, v4
	s_movk_i32 s7, 0x60
	s_movk_i32 s8, 0x80
	s_add_u32 s71, s42, 0x31600000
	v_bitop3_b32 v183, v10, s7, v9 bitop3:0x36
	v_bitop3_b32 v184, v10, s8, v9 bitop3:0x36
	v_bitop3_b32 v190, v4, s7, v9 bitop3:0x36
	v_bitop3_b32 v191, v4, s8, v9 bitop3:0x36
	s_addc_u32 s72, s43, 0
	s_sub_i32 s7, 0, s37
	v_readfirstlane_b32 s8, v1
	v_cmp_eq_u32_e64 s[4:5], 0, v2
	v_lshl_add_u32 v2, v171, 8, s10
	s_mul_i32 s7, s7, s8
	v_lshlrev_b32_e32 v11, 4, v11
	v_lshlrev_b32_e32 v12, 4, v12
	v_lshlrev_b32_e32 v13, 4, v13
	v_lshlrev_b32_e32 v5, 4, v5
	s_movk_i32 s11, 0xa0
	s_movk_i32 s12, 0xc0
	s_movk_i32 s13, 0xe0
	v_and_b32_e32 v0, 8, v3
	v_add_u32_e32 v3, 0x20000, v2
	v_and_b32_e32 v2, 16, v128
	s_mul_hi_u32 s7, s8, s7
	s_lshl_b32 s74, s6, 5
	s_mov_b32 s24, 2.0
	s_mov_b32 s26, 4.0
	s_mov_b32 s28, 0x40c00000
	v_or_b32_e32 v178, v10, v9
	v_or_b32_e32 v179, v4, v9
	s_mov_b32 s23, 0
	v_or_b32_e32 v180, 0xffffff80, v131
	v_bitop3_b32 v181, v10, 32, v9 bitop3:0x36
	v_bitop3_b32 v182, v10, 64, v9 bitop3:0x36
	v_bitop3_b32 v185, v10, s11, v9 bitop3:0x36
	v_bitop3_b32 v186, v10, s12, v9 bitop3:0x36
	v_bitop3_b32 v187, v10, s13, v9 bitop3:0x36
	v_bitop3_b32 v188, v4, 32, v9 bitop3:0x36
	v_bitop3_b32 v189, v4, 64, v9 bitop3:0x36
	v_bitop3_b32 v192, v4, s11, v9 bitop3:0x36
	v_bitop3_b32 v193, v4, s12, v9 bitop3:0x36
	v_bitop3_b32 v194, v4, s13, v9 bitop3:0x36
	s_add_i32 s73, s8, s7
	v_or_b32_e32 v195, s74, v6
	s_lshl_b32 s75, s6, 14
	v_lshl_or_b32 v196, s9, 4, v171
	s_add_i32 s76, s55, 0x2000
	s_add_i32 s77, s55, 0x4000
	s_add_i32 s78, s55, 0x6000
	s_add_i32 s79, s55, 0x8000
	s_add_i32 s80, s55, 0xa000
	s_add_i32 s81, s55, 0xc000
	s_add_i32 s82, s55, 0xe000
	s_mov_b32 s83, 0xc2fc0000
	v_lshlrev_b32_e32 v98, 1, v0
	s_mov_b32 s25, 0x40400000
	s_mov_b32 s27, 0x40a00000
	s_mov_b32 s29, 0x40e00000
	v_lshlrev_b32_e32 v100, 1, v2
	v_add_u32_e32 v197, v3, v5
	v_add_u32_e32 v198, v3, v13
	v_add_u32_e32 v199, v3, v12
	v_add_u32_e32 v200, v3, v11
	s_movk_i32 s84, 0x81
	s_mov_b32 s36, 0x3e0293ee
	v_mbcnt_hi_u32_b32 v201, -1, v129
	s_mov_b32 s85, 0xf149f2ca
	v_mov_b32_e32 v202, 0x42800000
	v_mov_b32_e32 v103, 0x3e0293ee
	v_mov_b32_e32 v203, 0xff61b1e6
	v_mov_b32_e32 v204, 0xf149f2ca
	s_mov_b32 s86, 0
	s_branch .LBB0_251

; __device__ __forceinline__ void attn_passes(const Params& p, LAS unsigned char* lds) {
;     ...
;                 const int k = 4 * n + (w >> 1) + j;
;                 LAS unsigned char* kb = lds + (k & 7) * 16384; LAS unsigned char* vb = kb + 8192;
;                 const int lb = Ls - 128 + 32 * k;
;                 bf16x8 kf[8]; s16x4 t0[8], t1[8];
;                 { const unsigned kbo = (unsigned)(size_t)kb;
;                   const unsigned k0 = kbo + koff[0], k1 = kbo + koff[1], k2 = kbo + koff[2], k3 = kbo + koff[3], k4 = kbo + koff[4], k5 = kbo + koff[5], k6 = kbo + koff[6], k7 = kbo + koff[7];
;                   asm volatile("ds_read_b128 %0, %8\n\tds_read_b128 %1, %9\n\tds_read_b128 %2, %10\n\tds_read_b128 %3, %11\n\tds_read_b128 %4, %12\n\tds_read_b128 %5, %13\n\tds_read_b128 %6, %14\n\tds_read_b128 %7, %15"
;                                : "=&v"(kf[0]), "=&v"(kf[4]), "=&v"(kf[1]), "=&v"(kf[5]), "=&v"(kf[2]), "=&v"(kf[6]), "=&v"(kf[3]), "=&v"(kf[7])
;                                : "v"(k0), "v"(k4), "v"(k1), "v"(k5), "v"(k2), "v"(k6), "v"(k3), "v"(k7) : "memory"); }
;                 const unsigned vbo = (unsigned)(size_t)vb;
;     ...
;                 TR_BATCH(0);
;                 asm volatile("s_waitcnt lgkmcnt(8)" : "+v"(kf[0]), "+v"(kf[1]), "+v"(kf[2]), "+v"(kf[3]), "+v"(kf[4]), "+v"(kf[5]), "+v"(kf[6]), "+v"(kf[7]) :: "memory");
;                 f32x4 s1 = (f32x4){0.f, 0.f, 0.f, 0.f}, s2 = s1;
; #pragma unroll
;                 for (int ks = 0; ks < 4; ++ks) {
;                     s1 = __builtin_amdgcn_mfma_f32_16x16x32_bf16(kf[ks], qf[ks], s1, 0, 0, 0); s2 = __builtin_amdgcn_mfma_f32_16x16x32_bf16(kf[4 + ks], qf[ks], s2, 0, 0, 0); }
;                 TR_BATCH(1);
;     ...
;                 const int rel0 = lq - lb - 8 * g;
;                 const float bias0 = -sd * (float)rel0;
;                 float sv[8];
;                 if (j >= 1 && j <= 3 && lb >= 0) {
; #pragma unroll
;                     for (int jj = 0; jj < 8; ++jj) { const float raw = jj < 4 ? s1[jj & 3] : s2[jj & 3]; sv[jj] = raw * sc2 + (bias0 + sd * (float)jj); }
;                 } else {
;                     const int lk0 = lb + 8 * g;
; #pragma unroll
;                     for (int jj = 0; jj < 8; ++jj) { const float raw = jj < 4 ? s1[jj & 3] : s2[jj & 3];
;                         const bool ok = ((unsigned)(rel0 - jj) <= 128u) && (lk0 + jj >= 0);
.LBB0_257:
	s_cmpk_lg_i32 s89, 0x180
	s_cselect_b64 s[10:11], -1, 0
	s_add_i32 s93, s75, s91
	s_add_i32 s6, s93, 0xfffd4000
	ds_read_b128 v[0:3], v197
	ds_read_b128 v[4:7], v198
	ds_read_b128 v[8:11], v199
	ds_read_b128 v[12:15], v200
	s_and_b32 s6, s6, 0x1c000
	s_add_i32 s6, s6, 0
	s_add_i32 s8, s6, 0x2000
	v_add_u32_e32 v48, s6, v135
	v_add_u32_e32 v49, s6, v139
	v_add_u32_e32 v50, s6, v174
	v_add_u32_e32 v51, s6, v176
	v_add_u32_e32 v52, s6, v137
	v_add_u32_e32 v53, s6, v141
	v_add_u32_e32 v54, s6, v175
	v_add_u32_e32 v55, s6, v177
	s_waitcnt lgkmcnt(0)
	ds_read_b128 v[16:19], v48
	ds_read_b128 v[32:35], v52
	ds_read_b128 v[20:23], v49
	ds_read_b128 v[36:39], v53
	ds_read_b128 v[24:27], v50
	ds_read_b128 v[40:43], v54
	ds_read_b128 v[28:31], v51
	ds_read_b128 v[44:47], v55
	v_add_u32_e32 v48, s8, v178
	v_add_u32_e32 v49, s8, v179
	v_add_u32_e32 v50, s8, v181
	v_add_u32_e32 v51, s8, v188
	v_add_u32_e32 v68, s8, v182
	v_add_u32_e32 v69, s8, v189
	v_add_u32_e32 v70, s8, v183
	v_add_u32_e32 v71, s8, v190
	ds_read_b64_tr_b16 v[64:65], v48
	ds_read_b64_tr_b16 v[66:67], v49
	ds_read_b64_tr_b16 v[60:61], v50
	ds_read_b64_tr_b16 v[62:63], v51
	ds_read_b64_tr_b16 v[56:57], v68
	ds_read_b64_tr_b16 v[58:59], v69
	ds_read_b64_tr_b16 v[52:53], v70
	ds_read_b64_tr_b16 v[54:55], v71
	s_waitcnt lgkmcnt(8)
	v_add_u32_e32 v90, s89, v206
	s_waitcnt lgkmcnt(0)
	v_mfma_f32_16x16x32_bf16 v[16:19], v[16:19], v[12:15], 0
	s_add_i32 s92, s90, s89
	s_add_i32 s6, s92, 0xffffff80
	v_xor_b32_e32 v158, 0x80000000, v111
	v_mfma_f32_16x16x32_bf16 v[16:19], v[20:23], v[8:11], v[16:19]
	s_cmp_gt_i32 s6, -1
	s_cselect_b64 s[6:7], -1, 0
	v_add_u32_e32 v48, s8, v187
	v_mfma_f32_16x16x32_bf16 v[16:19], v[24:27], v[4:7], v[16:19]
	v_add_u32_e32 v24, s89, v101
	v_sub_u32_e32 v208, v90, v24
	v_add_u32_e32 v24, 0x80, v208
	v_mfma_f32_16x16x32_bf16 v[16:19], v[28:31], v[0:3], v[16:19]
	v_cvt_f32_i32_e32 v102, v24
	v_cmp_gt_u32_e32 vcc, s84, v24
	s_and_b64 vcc, s[6:7], vcc
	v_mfma_f32_16x16x32_bf16 v[32:35], v[32:35], v[12:15], 0
	v_add_u32_e32 v49, s8, v194
	s_nop 2
	v_mov_b32_e32 v159, v16
	v_pk_mul_f32 v[24:25], v[158:159], v[102:103]
	v_mfma_f32_16x16x32_bf16 v[20:23], v[36:39], v[8:11], v[32:35]
	v_add_f32_e32 v16, v110, v24
	v_add_f32_e32 v16, v16, v25
	v_add_u32_e32 v102, s89, v99
	v_cndmask_b32_e32 v32, v203, v16, vcc
	v_add_u32_e32 v16, 0x7f, v208
	v_cmp_gt_u32_e32 vcc, s84, v16
	v_add_f32_e32 v16, v111, v24
	v_fmac_f32_e32 v16, 0x3e0293ee, v17
	s_and_b64 vcc, s[6:7], vcc
	v_mfma_f32_16x16x32_bf16 v[20:23], v[40:43], v[4:7], v[20:23]
	v_cndmask_b32_e32 v33, v203, v16, vcc
	v_add_u32_e32 v16, 0x7e, v208
	v_cmp_gt_u32_e32 vcc, s84, v16
	v_add_f32_e32 v16, v112, v24
	v_fmac_f32_e32 v16, 0x3e0293ee, v18
	s_and_b64 vcc, s[6:7], vcc
	v_cndmask_b32_e32 v34, v203, v16, vcc
	v_add_u32_e32 v16, 0x7d, v208
	v_mfma_f32_16x16x32_bf16 v[20:23], v[44:47], v[0:3], v[20:23]
	v_cmp_gt_u32_e32 vcc, s84, v16
	v_add_f32_e32 v16, v113, v24
	v_fmac_f32_e32 v16, 0x3e0293ee, v19
	s_and_b64 vcc, s[6:7], vcc
	v_cndmask_b32_e32 v35, v203, v16, vcc
	v_add_u32_e32 v16, 0x7c, v208
	v_cmp_gt_u32_e32 vcc, s84, v16
	v_add_f32_e32 v16, v114, v24
	v_fmac_f32_e32 v16, 0x3e0293ee, v20
	s_and_b64 vcc, s[6:7], vcc
	v_cndmask_b32_e32 v36, v203, v16, vcc
	v_add_u32_e32 v16, 0x7b, v208
	v_cmp_gt_u32_e32 vcc, s84, v16
	v_add_f32_e32 v16, v115, v24
	v_fmac_f32_e32 v16, 0x3e0293ee, v21
	s_and_b64 vcc, s[6:7], vcc
	v_cndmask_b32_e32 v37, v203, v16, vcc
	v_add_u32_e32 v16, 0x7a, v208
	v_cmp_gt_u32_e32 vcc, s84, v16
	v_add_f32_e32 v16, v116, v24
	v_fmac_f32_e32 v16, 0x3e0293ee, v22
	s_and_b64 vcc, s[6:7], vcc
	v_cndmask_b32_e32 v38, v203, v16, vcc
	v_add_u32_e32 v16, 0x79, v208
	v_cmp_gt_u32_e32 vcc, s84, v16
	v_add_f32_e32 v16, v117, v24
	v_fmac_f32_e32 v16, 0x3e0293ee, v23
	s_and_b64 vcc, s[6:7], vcc
	v_cndmask_b32_e32 v39, v203, v16, vcc
	v_max_f32_e32 v18, v38, v39
	v_max_f32_e32 v16, v32, v33
	v_max_f32_e32 v17, v34, v35
	v_max3_f32 v18, v36, v37, v18
	v_max3_f32 v16, v16, v17, v18
	v_add_u32_e32 v40, s8, v184
	v_add_u32_e32 v41, s8, v191
	v_mov_b32_e32 v17, v16
	v_add_u32_e32 v42, s8, v185
	v_add_u32_e32 v43, s8, v192
	v_add_u32_e32 v44, s8, v186
	v_add_u32_e32 v45, s8, v193
	v_permlane16_swap_b32_e32 v16, v17
	v_max_f32_e32 v16, v16, v17
	v_mov_b32_e32 v17, v16
	v_mov_b32_e32 v18, v16
	s_nop 1
	v_permlane32_swap_b32_e32 v17, v18
	v_max_f32_e32 v16, v17, v18
	v_cmp_lt_f32_e32 vcc, s85, v16
	s_cmp_eq_u64 vcc, 0
	v_max_f32_e32 v46, 0xf149f2ca, v16
	s_cselect_b64 vcc, -1, 0
	v_cndmask_b32_e32 v160, v46, v204, vcc
	v_sub_f32_e32 v32, v32, v160
	v_exp_f32_e32 v215, v32
	v_sub_f32_e32 v32, v33, v160
	v_sub_f32_e32 v16, 0xf149f2ca, v46
	v_exp_f32_e32 v159, v32
	v_sub_f32_e32 v32, v34, v160
	v_exp_f32_e32 v47, v16
	v_exp_f32_e32 v209, v32
	v_sub_f32_e32 v32, v35, v160
	v_exp_f32_e32 v211, v32
	v_sub_f32_e32 v32, v36, v160
	v_exp_f32_e32 v213, v32
	v_sub_f32_e32 v32, v37, v160
	v_exp_f32_e32 v210, v32
	v_sub_f32_e32 v32, v38, v160
	ds_read_b64_tr_b16 v[28:29], v40
	ds_read_b64_tr_b16 v[30:31], v41
	ds_read_b64_tr_b16 v[24:25], v42
	ds_read_b64_tr_b16 v[26:27], v43
	ds_read_b64_tr_b16 v[20:21], v44
	ds_read_b64_tr_b16 v[22:23], v45
	ds_read_b64_tr_b16 v[16:17], v48
	ds_read_b64_tr_b16 v[18:19], v49
	v_mul_f32_e32 v40, 0, v47
	v_exp_f32_e32 v212, v32
	v_sub_f32_e32 v32, v39, v160
	v_cndmask_b32_e64 v48, v40, 0, vcc
	v_exp_f32_e32 v214, v32
	v_cvt_pk_bf16_f32 v68, v215, v159
	v_cvt_pk_bf16_f32 v69, v209, v211
	v_cvt_pk_bf16_f32 v70, v213, v210
	v_cvt_pk_bf16_f32 v71, v212, v214
	s_waitcnt lgkmcnt(0)
	v_mov_b32_e32 v49, v48
	v_mov_b32_e32 v50, v48
	v_mov_b32_e32 v51, v48
	s_barrier
; #define AT_WAITV(n) asm volatile("s_waitcnt vmcnt(" #n ")" ::: "memory")
; __device__ __forceinline__ void attn_passes(const Params& p, LAS unsigned char* lds) {
;     ...
; #pragma unroll
;                 for (int c = 0; c < 8; ++c) {
;                     const bf16x8 va = (bf16x8){t0[c][0], t0[c][1], t0[c][2], t0[c][3], t1[c][0], t1[c][1], t1[c][2], t1[c][3]};
;                     o[c] = __builtin_amdgcn_mfma_f32_16x16x32_bf16(va, pb, o[c], 0, 0, 0); }
;                 if (j == 4) { if (n < 3) AT_WAITV(6); }
	s_cmpk_eq_i32 s89, 0x180
	v_mfma_f32_16x16x32_bf16 v[44:47], v[64:67], v[68:71], v[48:51]
	v_mfma_f32_16x16x32_bf16 v[40:43], v[60:63], v[68:71], v[48:51]
	v_mfma_f32_16x16x32_bf16 v[36:39], v[56:59], v[68:71], v[48:51]
	v_mfma_f32_16x16x32_bf16 v[32:35], v[52:55], v[68:71], v[48:51]
	v_mfma_f32_16x16x32_bf16 v[28:31], v[28:31], v[68:71], v[48:51]
	v_mfma_f32_16x16x32_bf16 v[24:27], v[24:27], v[68:71], v[48:51]
	v_mfma_f32_16x16x32_bf16 v[20:23], v[20:23], v[68:71], v[48:51]
	v_mfma_f32_16x16x32_bf16 v[16:19], v[16:19], v[68:71], v[48:51]
	s_cbranch_scc1 .LBB0_259
	s_nop 1
	v_add_u32_e32 v50, 0x80, v102
	v_max_i32_e32 v50, 0, v50
	v_min_i32_e32 v50, s88, v50
	v_mov_b32_e32 v51, v91
	v_lshlrev_b64 v[50:51], s87, v[50:51]
	s_add_i32 s6, s91, 0xffff4000
	v_lshl_add_u64 v[50:51], v[50:51], 0, s[22:23]
	s_and_b32 s6, s6, 0x10000
	v_lshlrev_b64 v[50:51], 8, v[50:51]
	s_add_i32 s6, s55, s6
	v_add_u32_e32 v49, s89, v205
	v_lshl_add_u64 v[52:53], v[104:105], 0, v[50:51]
	s_mov_b32 m0, s6
	v_add_u32_e32 v54, 0x80, v49
	global_load_lds_dwordx4 v[52:53], off
	v_lshl_add_u64 v[50:51], v[106:107], 0, v[50:51]
	s_add_i32 m0, s6, 0x2000
	s_nop 0
	global_load_lds_dwordx4 v[50:51], off
	v_min_i32_e32 v50, s88, v54
	v_ashrrev_i32_e32 v51, 31, v50
	v_lshlrev_b64 v[50:51], s87, v[50:51]
	v_lshl_add_u64 v[50:51], v[50:51], 0, s[22:23]
	v_lshlrev_b64 v[50:51], 8, v[50:51]
	v_lshl_add_u64 v[50:51], v[108:109], 0, v[50:51]
	s_mov_b32 m0, s56
	s_mov_b64 s[6:7], -1
	global_load_lds_dwordx4 v[50:51], off
	v_add_u32_e32 v50, 0xa0, v49
	v_min_i32_e32 v50, s88, v50
	v_ashrrev_i32_e32 v51, 31, v50
	v_lshlrev_b64 v[50:51], s87, v[50:51]
	v_lshl_add_u64 v[50:51], v[50:51], 0, s[22:23]
	v_lshlrev_b64 v[50:51], 8, v[50:51]
	v_lshl_add_u64 v[50:51], v[108:109], 0, v[50:51]
	s_mov_b32 m0, s66
	s_nop 0
	global_load_lds_dwordx4 v[50:51], off
	v_add_u32_e32 v50, 0xc0, v49
	v_min_i32_e32 v50, s88, v50
	v_ashrrev_i32_e32 v51, 31, v50
	v_lshlrev_b64 v[50:51], s87, v[50:51]
	v_lshl_add_u64 v[50:51], v[50:51], 0, s[22:23]
	v_lshlrev_b64 v[50:51], 8, v[50:51]
	v_lshl_add_u64 v[50:51], v[108:109], 0, v[50:51]
	s_mov_b32 m0, s67
	v_add_u32_e32 v49, 0xe0, v49
	global_load_lds_dwordx4 v[50:51], off
	v_min_i32_e32 v50, s88, v49
	v_ashrrev_i32_e32 v51, 31, v50
	v_lshlrev_b64 v[50:51], s87, v[50:51]
	v_lshl_add_u64 v[50:51], v[50:51], 0, s[22:23]
	v_lshlrev_b64 v[50:51], 8, v[50:51]
	v_lshl_add_u64 v[50:51], v[108:109], 0, v[50:51]
	s_cbranch_execz .LBB0_260
	s_branch .LBB0_263

; __device__ __forceinline__ void attn_passes(const Params& p, LAS unsigned char* lds) {
;     ...
;                 float cmax = fmaxf(fmaxf(fmaxf(sv[0], sv[1]), fmaxf(sv[2], sv[3])), fmaxf(fmaxf(sv[4], sv[5]), fmaxf(sv[6], sv[7])));
;                 cmax = fmaxf(cmax, __shfl_xor(cmax, 16)); cmax = fmaxf(cmax, __shfl_xor(cmax, 32));
;                 if (__any(cmax > m + 8.0f)) {
;                     const float mnew = fmaxf(m, cmax), alpha = __builtin_amdgcn_exp2f(m - mnew); m = mnew;
;                     lsum *= alpha;
; #pragma unroll
;                     for (int c = 0; c < 8; ++c) o[c] *= alpha;
;                 }
;                 float pe[8], psum = 0.f;
; #pragma unroll
;                 for (int jj = 0; jj < 8; ++jj) { pe[jj] = __builtin_amdgcn_exp2f(sv[jj] - m); psum += pe[jj]; }
;                 lsum += psum;
.LBB0_268:
	v_max_f32_e32 v84, v163, v163
	v_max_f32_e32 v85, v162, v162
	v_add_f32_e32 v49, 0, v215
	v_max_f32_e32 v84, v85, v84
	v_max_f32_e32 v85, v89, v89
	v_max_f32_e32 v215, v88, v88
	v_max_f32_e32 v85, v215, v85
	v_max_f32_e32 v215, v83, v83
	v_max_f32_e32 v216, v82, v82
	v_max_f32_e32 v215, v216, v215
	v_max3_f32 v215, v86, v87, v215
	v_max3_f32 v84, v84, v85, v215
	v_mov_b32_e32 v85, v84
	v_add_f32_e32 v49, v159, v49
	v_add_f32_e32 v49, v209, v49
	v_add_f32_e32 v49, v211, v49
	v_add_f32_e32 v49, v213, v49
	v_permlane16_swap_b32_e32 v84, v85
	v_max_f32_e32 v84, v84, v85
	v_mov_b32_e32 v85, v84
	v_add_f32_e32 v49, v210, v49
	v_add_f32_e32 v49, v212, v49
	v_add_f32_e32 v49, v214, v49
	v_add_f32_e32 v159, v48, v49
	v_mov_b32_e32 v48, v84
	s_nop 1
	v_permlane32_swap_b32_e32 v48, v85
	v_max_f32_e32 v48, v48, v85
	v_add_f32_e32 v49, 0x41000000, v160
	v_cmp_gt_f32_e32 vcc, v48, v49
	s_cbranch_vccz .LBB0_270
	v_max_f32_e32 v48, v48, v48
	v_max_f32_e32 v49, v160, v160
	v_max_f32_e32 v49, v49, v48
	v_sub_f32_e32 v48, v160, v49
	v_exp_f32_e32 v48, v48
	v_mov_b32_e32 v160, v49
	v_pk_mul_f32 v[46:47], v[46:47], v[48:49] op_sel_hi:[1,0]
	v_pk_mul_f32 v[44:45], v[44:45], v[48:49] op_sel_hi:[1,0]
	v_pk_mul_f32 v[42:43], v[42:43], v[48:49] op_sel_hi:[1,0]
	v_pk_mul_f32 v[40:41], v[40:41], v[48:49] op_sel_hi:[1,0]
	v_pk_mul_f32 v[38:39], v[38:39], v[48:49] op_sel_hi:[1,0]
	v_pk_mul_f32 v[36:37], v[36:37], v[48:49] op_sel_hi:[1,0]
	v_pk_mul_f32 v[34:35], v[34:35], v[48:49] op_sel_hi:[1,0]
	v_pk_mul_f32 v[32:33], v[32:33], v[48:49] op_sel_hi:[1,0]
	v_pk_mul_f32 v[30:31], v[30:31], v[48:49] op_sel_hi:[1,0]
	v_pk_mul_f32 v[28:29], v[28:29], v[48:49] op_sel_hi:[1,0]
	v_pk_mul_f32 v[26:27], v[26:27], v[48:49] op_sel_hi:[1,0]
	v_pk_mul_f32 v[24:25], v[24:25], v[48:49] op_sel_hi:[1,0]
	v_pk_mul_f32 v[22:23], v[22:23], v[48:49] op_sel_hi:[1,0]
	v_pk_mul_f32 v[20:21], v[20:21], v[48:49] op_sel_hi:[1,0]
	v_pk_mul_f32 v[18:19], v[18:19], v[48:49] op_sel_hi:[1,0]
	v_pk_mul_f32 v[16:17], v[16:17], v[48:49] op_sel_hi:[1,0]
	v_mul_f32_e32 v159, v159, v48

; __device__ __forceinline__ void attn_passes(const Params& p, LAS unsigned char* lds) {
;     ...
;                 float cmax = fmaxf(fmaxf(fmaxf(sv[0], sv[1]), fmaxf(sv[2], sv[3])), fmaxf(fmaxf(sv[4], sv[5]), fmaxf(sv[6], sv[7])));
;                 cmax = fmaxf(cmax, __shfl_xor(cmax, 16)); cmax = fmaxf(cmax, __shfl_xor(cmax, 32));
;                 if (__any(cmax > m + 8.0f)) {
;                     const float mnew = fmaxf(m, cmax), alpha = __builtin_amdgcn_exp2f(m - mnew); m = mnew;
;                     lsum *= alpha;
; #pragma unroll
;                     for (int c = 0; c < 8; ++c) o[c] *= alpha;
;                 }
;                 float pe[8], psum = 0.f;
; #pragma unroll
;                 for (int jj = 0; jj < 8; ++jj) { pe[jj] = __builtin_amdgcn_exp2f(sv[jj] - m); psum += pe[jj]; }
;                 lsum += psum;
.LBB0_283:
	v_add_f32_e32 v82, 0, v214
	v_max_f32_e32 v83, v89, v89
	v_max_f32_e32 v214, v88, v88
	v_max_f32_e32 v83, v214, v83
	v_max_f32_e32 v214, v87, v87
	v_max_f32_e32 v215, v86, v86
	v_max_f32_e32 v214, v215, v214
	v_max_f32_e32 v215, v81, v81
	v_max_f32_e32 v216, v80, v80
	v_max_f32_e32 v215, v216, v215
	v_max3_f32 v215, v84, v85, v215
	v_max3_f32 v83, v83, v214, v215
	v_mov_b32_e32 v214, v83
	v_add_f32_e32 v82, v162, v82
	v_add_f32_e32 v82, v163, v82
	v_add_f32_e32 v82, v210, v82
	v_add_f32_e32 v82, v212, v82
	v_permlane16_swap_b32_e32 v83, v214
	v_max_f32_e32 v83, v83, v214
	v_mov_b32_e32 v162, v83
	v_add_f32_e32 v82, v209, v82
	v_add_f32_e32 v82, v211, v82
	v_add_f32_e32 v82, v213, v82
	v_add_f32_e32 v159, v159, v82
	v_mov_b32_e32 v82, v83
	s_nop 1
	v_permlane32_swap_b32_e32 v82, v162
	v_max_f32_e32 v82, v82, v162
	v_add_f32_e32 v83, 0x41000000, v160
	v_cmp_gt_f32_e32 vcc, v82, v83
	s_cbranch_vccz .LBB0_285
	v_max_f32_e32 v82, v82, v82
	v_max_f32_e32 v83, v160, v160
	v_max_f32_e32 v83, v83, v82
	v_sub_f32_e32 v82, v160, v83
	v_exp_f32_e32 v82, v82
	v_mov_b32_e32 v160, v83
	v_pk_mul_f32 v[46:47], v[46:47], v[82:83] op_sel_hi:[1,0]
	v_pk_mul_f32 v[44:45], v[44:45], v[82:83] op_sel_hi:[1,0]
	v_pk_mul_f32 v[42:43], v[42:43], v[82:83] op_sel_hi:[1,0]
	v_pk_mul_f32 v[40:41], v[40:41], v[82:83] op_sel_hi:[1,0]
	v_pk_mul_f32 v[38:39], v[38:39], v[82:83] op_sel_hi:[1,0]
	v_pk_mul_f32 v[36:37], v[36:37], v[82:83] op_sel_hi:[1,0]
	v_pk_mul_f32 v[34:35], v[34:35], v[82:83] op_sel_hi:[1,0]
	v_pk_mul_f32 v[32:33], v[32:33], v[82:83] op_sel_hi:[1,0]
	v_pk_mul_f32 v[30:31], v[30:31], v[82:83] op_sel_hi:[1,0]
	v_pk_mul_f32 v[28:29], v[28:29], v[82:83] op_sel_hi:[1,0]
	v_pk_mul_f32 v[26:27], v[26:27], v[82:83] op_sel_hi:[1,0]
	v_pk_mul_f32 v[24:25], v[24:25], v[82:83] op_sel_hi:[1,0]
	v_pk_mul_f32 v[22:23], v[22:23], v[82:83] op_sel_hi:[1,0]
	v_pk_mul_f32 v[20:21], v[20:21], v[82:83] op_sel_hi:[1,0]
	v_pk_mul_f32 v[18:19], v[18:19], v[82:83] op_sel_hi:[1,0]
	v_pk_mul_f32 v[16:17], v[16:17], v[82:83] op_sel_hi:[1,0]
	v_mul_f32_e32 v159, v159, v82

; __device__ __forceinline__ void attn_passes(const Params& p, LAS unsigned char* lds) {
;     ...
;                 float cmax = fmaxf(fmaxf(fmaxf(sv[0], sv[1]), fmaxf(sv[2], sv[3])), fmaxf(fmaxf(sv[4], sv[5]), fmaxf(sv[6], sv[7])));
;                 cmax = fmaxf(cmax, __shfl_xor(cmax, 16)); cmax = fmaxf(cmax, __shfl_xor(cmax, 32));
;                 if (__any(cmax > m + 8.0f)) {
;                     const float mnew = fmaxf(m, cmax), alpha = __builtin_amdgcn_exp2f(m - mnew); m = mnew;
;                     lsum *= alpha;
; #pragma unroll
;                     for (int c = 0; c < 8; ++c) o[c] *= alpha;
;                 }
;                 float pe[8], psum = 0.f;
; #pragma unroll
;                 for (int jj = 0; jj < 8; ++jj) { pe[jj] = __builtin_amdgcn_exp2f(sv[jj] - m); psum += pe[jj]; }
;                 lsum += psum;
.LBB0_298:
	v_add_f32_e32 v82, 0, v214
	v_max_f32_e32 v83, v89, v89
	v_max_f32_e32 v214, v88, v88
	v_max_f32_e32 v83, v214, v83
	v_max_f32_e32 v214, v87, v87
	v_max_f32_e32 v215, v86, v86
	v_max_f32_e32 v214, v215, v214
	v_max_f32_e32 v215, v81, v81
	v_max_f32_e32 v216, v80, v80
	v_max_f32_e32 v215, v216, v215
	v_max3_f32 v215, v84, v85, v215
	v_max3_f32 v83, v83, v214, v215
	v_mov_b32_e32 v214, v83
	v_add_f32_e32 v82, v162, v82
	v_add_f32_e32 v82, v163, v82
	v_add_f32_e32 v82, v210, v82
	v_add_f32_e32 v82, v212, v82
	v_permlane16_swap_b32_e32 v83, v214
	v_max_f32_e32 v83, v83, v214
	v_mov_b32_e32 v162, v83
	v_add_f32_e32 v82, v209, v82
	v_add_f32_e32 v82, v211, v82
	v_add_f32_e32 v82, v213, v82
	v_add_f32_e32 v82, v159, v82
	v_mov_b32_e32 v159, v83
	s_nop 1
	v_permlane32_swap_b32_e32 v159, v162
	v_max_f32_e32 v83, v159, v162
	v_add_f32_e32 v159, 0x41000000, v160
	v_cmp_gt_f32_e32 vcc, v83, v159
	s_cbranch_vccz .LBB0_300
	v_max_f32_e32 v83, v83, v83
	v_max_f32_e32 v159, v160, v160
	v_max_f32_e32 v83, v159, v83
	v_sub_f32_e32 v159, v160, v83
	v_exp_f32_e32 v160, v159
	s_nop 0
	v_pk_mul_f32 v[46:47], v[46:47], v[160:161] op_sel_hi:[1,0]
	v_pk_mul_f32 v[44:45], v[44:45], v[160:161] op_sel_hi:[1,0]
	v_pk_mul_f32 v[42:43], v[42:43], v[160:161] op_sel_hi:[1,0]
	v_pk_mul_f32 v[40:41], v[40:41], v[160:161] op_sel_hi:[1,0]
	v_pk_mul_f32 v[38:39], v[38:39], v[160:161] op_sel_hi:[1,0]
	v_pk_mul_f32 v[36:37], v[36:37], v[160:161] op_sel_hi:[1,0]
	v_pk_mul_f32 v[34:35], v[34:35], v[160:161] op_sel_hi:[1,0]
	v_pk_mul_f32 v[32:33], v[32:33], v[160:161] op_sel_hi:[1,0]
	v_pk_mul_f32 v[30:31], v[30:31], v[160:161] op_sel_hi:[1,0]
	v_pk_mul_f32 v[28:29], v[28:29], v[160:161] op_sel_hi:[1,0]
	v_pk_mul_f32 v[26:27], v[26:27], v[160:161] op_sel_hi:[1,0]
	v_pk_mul_f32 v[24:25], v[24:25], v[160:161] op_sel_hi:[1,0]
	v_pk_mul_f32 v[22:23], v[22:23], v[160:161] op_sel_hi:[1,0]
	v_pk_mul_f32 v[20:21], v[20:21], v[160:161] op_sel_hi:[1,0]
	v_pk_mul_f32 v[18:19], v[18:19], v[160:161] op_sel_hi:[1,0]
	v_pk_mul_f32 v[16:17], v[16:17], v[160:161] op_sel_hi:[1,0]
	v_mul_f32_e32 v82, v82, v160
	v_mov_b32_e32 v160, v83

; __device__ __forceinline__ void attn_passes(const Params& p, LAS unsigned char* lds) {
;     ...
;                 const int k = 4 * n + (w >> 1) + j;
;                 LAS unsigned char* kb = lds + (k & 7) * 16384; LAS unsigned char* vb = kb + 8192;
;                 const int lb = Ls - 128 + 32 * k;
;                 bf16x8 kf[8]; s16x4 t0[8], t1[8];
;                 { const unsigned kbo = (unsigned)(size_t)kb;
;                   const unsigned k0 = kbo + koff[0], k1 = kbo + koff[1], k2 = kbo + koff[2], k3 = kbo + koff[3], k4 = kbo + koff[4], k5 = kbo + koff[5], k6 = kbo + koff[6], k7 = kbo + koff[7];
;                   asm volatile("ds_read_b128 %0, %8\n\tds_read_b128 %1, %9\n\tds_read_b128 %2, %10\n\tds_read_b128 %3, %11\n\tds_read_b128 %4, %12\n\tds_read_b128 %5, %13\n\tds_read_b128 %6, %14\n\tds_read_b128 %7, %15"
;                                : "=&v"(kf[0]), "=&v"(kf[4]), "=&v"(kf[1]), "=&v"(kf[5]), "=&v"(kf[2]), "=&v"(kf[6]), "=&v"(kf[3]), "=&v"(kf[7])
;                                : "v"(k0), "v"(k4), "v"(k1), "v"(k5), "v"(k2), "v"(k6), "v"(k3), "v"(k7) : "memory"); }
;                 const unsigned vbo = (unsigned)(size_t)vb;
;     ...
;                 TR_BATCH(0);
;                 asm volatile("s_waitcnt lgkmcnt(8)" : "+v"(kf[0]), "+v"(kf[1]), "+v"(kf[2]), "+v"(kf[3]), "+v"(kf[4]), "+v"(kf[5]), "+v"(kf[6]), "+v"(kf[7]) :: "memory");
;                 f32x4 s1 = (f32x4){0.f, 0.f, 0.f, 0.f}, s2 = s1;
; #pragma unroll
;                 for (int ks = 0; ks < 4; ++ks) {
;                     s1 = __builtin_amdgcn_mfma_f32_16x16x32_bf16(kf[ks], qf[ks], s1, 0, 0, 0); s2 = __builtin_amdgcn_mfma_f32_16x16x32_bf16(kf[4 + ks], qf[ks], s2, 0, 0, 0); }
;                 TR_BATCH(1);
;     ...
;                 const int rel0 = lq - lb - 8 * g;
;                 const float bias0 = -sd * (float)rel0;
;                 float sv[8];
;                 if (j >= 1 && j <= 3 && lb >= 0) {
; #pragma unroll
;                     for (int jj = 0; jj < 8; ++jj) { const float raw = jj < 4 ? s1[jj & 3] : s2[jj & 3]; sv[jj] = raw * sc2 + (bias0 + sd * (float)jj); }
;                 } else {
;                     const int lk0 = lb + 8 * g;
; #pragma unroll
;                     for (int jj = 0; jj < 8; ++jj) { const float raw = jj < 4 ? s1[jj & 3] : s2[jj & 3];
;                         const bool ok = ((unsigned)(rel0 - jj) <= 128u) && (lk0 + jj >= 0);
.LBB0_310:
	s_add_i32 s93, s93, 0xfffe4000
	s_and_b32 s8, s93, 0x1c000
	s_add_i32 s8, s8, 0
	s_add_i32 s10, s8, 0x2000
	v_add_u32_e32 v48, s8, v135
	v_add_u32_e32 v49, s8, v139
	v_add_u32_e32 v50, s8, v174
	v_add_u32_e32 v51, s8, v176
	v_add_u32_e32 v52, s8, v137
	v_add_u32_e32 v53, s8, v141
	v_add_u32_e32 v54, s8, v175
	v_add_u32_e32 v55, s8, v177
	ds_read_b128 v[64:67], v48
	ds_read_b128 v[210:213], v52
	ds_read_b128 v[68:71], v49
	ds_read_b128 v[214:217], v53
	ds_read_b128 v[72:75], v50
	ds_read_b128 v[218:221], v54
	ds_read_b128 v[76:79], v51
	ds_read_b128 v[222:225], v55
	v_add_u32_e32 v89, s10, v178
	v_add_u32_e32 v102, s10, v179
	v_add_u32_e32 v159, s10, v181
	v_add_u32_e32 v162, s10, v188
	v_add_u32_e32 v163, s10, v182
	v_add_u32_e32 v209, s10, v189
	v_add_u32_e32 v226, s10, v183
	v_add_u32_e32 v227, s10, v190
	ds_read_b64_tr_b16 v[60:61], v89
	ds_read_b64_tr_b16 v[62:63], v102
	ds_read_b64_tr_b16 v[56:57], v159
	ds_read_b64_tr_b16 v[58:59], v162
	ds_read_b64_tr_b16 v[52:53], v163
	ds_read_b64_tr_b16 v[54:55], v209
	ds_read_b64_tr_b16 v[48:49], v226
	ds_read_b64_tr_b16 v[50:51], v227
	s_waitcnt lgkmcnt(8)
	v_cvt_f32_i32_e32 v102, v208
	v_mfma_f32_16x16x32_bf16 v[64:67], v[64:67], v[12:15], 0
	s_cmp_gt_i32 s92, -1
	s_cselect_b64 s[8:9], -1, 0
	v_cmp_gt_u32_e32 vcc, s84, v208
	v_mfma_f32_16x16x32_bf16 v[12:15], v[210:213], v[12:15], 0
	s_and_b64 vcc, s[8:9], vcc
	v_mfma_f32_16x16x32_bf16 v[64:67], v[68:71], v[8:11], v[64:67]
	v_mfma_f32_16x16x32_bf16 v[8:11], v[214:217], v[8:11], v[12:15]
	v_mfma_f32_16x16x32_bf16 v[12:15], v[72:75], v[4:7], v[64:67]
	v_add_u32_e32 v73, s10, v184
	v_add_u32_e32 v74, s10, v191
	v_add_u32_e32 v75, s10, v185
	s_nop 2
	v_add_f32_e32 v64, 0, v83
	v_add_f32_e32 v64, v88, v64
	v_add_f32_e32 v64, v86, v64
	v_mfma_f32_16x16x32_bf16 v[4:7], v[218:221], v[4:7], v[8:11]
	s_nop 2
	v_add_f32_e32 v8, v87, v64
	v_add_f32_e32 v8, v84, v8
	v_add_f32_e32 v64, v85, v8
	v_mfma_f32_16x16x32_bf16 v[8:11], v[76:79], v[0:3], v[12:15]
	v_add_u32_e32 v76, s10, v192
	v_add_u32_e32 v77, s10, v186
	v_mfma_f32_16x16x32_bf16 v[0:3], v[222:225], v[0:3], v[4:7]
	v_add_f32_e32 v12, v80, v64
	s_nop 3
	v_mov_b32_e32 v159, v8
	v_add_f32_e32 v12, v81, v12
	v_pk_mul_f32 v[4:5], v[158:159], v[102:103]
	v_add_f32_e32 v64, v82, v12
	v_add_f32_e32 v6, v110, v4
	v_add_f32_e32 v5, v6, v5
	v_cndmask_b32_e32 v65, v203, v5, vcc
	v_add_u32_e32 v5, -1, v208
	v_cmp_gt_u32_e32 vcc, s84, v5
	v_add_f32_e32 v5, v111, v4
	v_fmac_f32_e32 v5, 0x3e0293ee, v9
	s_and_b64 vcc, s[8:9], vcc
	v_cndmask_b32_e32 v66, v203, v5, vcc
	v_add_u32_e32 v5, -2, v208
	v_cmp_gt_u32_e32 vcc, s84, v5
	v_add_f32_e32 v5, v112, v4
	v_fmac_f32_e32 v5, 0x3e0293ee, v10
	s_and_b64 vcc, s[8:9], vcc
	v_cndmask_b32_e32 v67, v203, v5, vcc
	v_add_u32_e32 v5, -3, v208
	v_cmp_gt_u32_e32 vcc, s84, v5
	v_add_f32_e32 v5, v113, v4
	v_fmac_f32_e32 v5, 0x3e0293ee, v11
	s_and_b64 vcc, s[8:9], vcc
	v_cndmask_b32_e32 v68, v203, v5, vcc
	v_add_u32_e32 v5, -4, v208
	v_cmp_gt_u32_e32 vcc, s84, v5
	v_add_f32_e32 v5, v114, v4
	v_fmac_f32_e32 v5, 0x3e0293ee, v0
	s_and_b64 vcc, s[8:9], vcc
	v_add_u32_e32 v0, -5, v208
	v_cndmask_b32_e32 v69, v203, v5, vcc
	v_cmp_gt_u32_e32 vcc, s84, v0
	v_add_f32_e32 v0, v115, v4
	v_fmac_f32_e32 v0, 0x3e0293ee, v1
	s_and_b64 vcc, s[8:9], vcc
	v_cndmask_b32_e32 v70, v203, v0, vcc
	v_add_u32_e32 v0, -6, v208
	v_cmp_gt_u32_e32 vcc, s84, v0
	v_add_f32_e32 v0, v116, v4
	v_fmac_f32_e32 v0, 0x3e0293ee, v2
	s_and_b64 vcc, s[8:9], vcc
	v_cndmask_b32_e32 v71, v203, v0, vcc
	v_add_u32_e32 v0, -7, v208
	v_cmp_gt_u32_e32 vcc, s84, v0
	v_add_f32_e32 v0, v117, v4
	v_fmac_f32_e32 v0, 0x3e0293ee, v3
	s_and_b64 vcc, s[8:9], vcc
	v_cndmask_b32_e32 v72, v203, v0, vcc
	v_max_f32_e32 v2, v71, v72
	v_max_f32_e32 v0, v65, v66
	v_max_f32_e32 v1, v67, v68
	v_max3_f32 v2, v69, v70, v2
	v_max3_f32 v0, v0, v1, v2
	v_mov_b32_e32 v1, v0
	v_add_u32_e32 v80, s10, v193
	v_add_u32_e32 v81, s10, v187
	v_add_u32_e32 v82, s10, v194
	v_permlane16_swap_b32_e32 v0, v1
	v_max_f32_e32 v78, v0, v1
	v_mov_b32_e32 v79, v78
	ds_read_b64_tr_b16 v[12:13], v73
	ds_read_b64_tr_b16 v[14:15], v74
	ds_read_b64_tr_b16 v[8:9], v75
	ds_read_b64_tr_b16 v[10:11], v76
	ds_read_b64_tr_b16 v[4:5], v77
	ds_read_b64_tr_b16 v[6:7], v80
	ds_read_b64_tr_b16 v[0:1], v81
	ds_read_b64_tr_b16 v[2:3], v82
	v_add_f32_e32 v74, 0x41000000, v160
	v_mov_b32_e32 v73, v78
	s_nop 1
	v_permlane32_swap_b32_e32 v73, v79
	v_max_f32_e32 v73, v73, v79
	v_cmp_gt_f32_e32 vcc, v73, v74
	s_cbranch_vccz .LBB0_312
	v_max_f32_e32 v73, v73, v73
	v_max_f32_e32 v74, v160, v160
	v_max_f32_e32 v73, v74, v73
	v_sub_f32_e32 v74, v160, v73
	v_exp_f32_e32 v74, v74
	v_mov_b32_e32 v160, v73
	v_pk_mul_f32 v[46:47], v[46:47], v[74:75] op_sel_hi:[1,0]
	v_pk_mul_f32 v[44:45], v[44:45], v[74:75] op_sel_hi:[1,0]
	v_pk_mul_f32 v[42:43], v[42:43], v[74:75] op_sel_hi:[1,0]
	v_pk_mul_f32 v[40:41], v[40:41], v[74:75] op_sel_hi:[1,0]
	v_pk_mul_f32 v[38:39], v[38:39], v[74:75] op_sel_hi:[1,0]
	v_pk_mul_f32 v[36:37], v[36:37], v[74:75] op_sel_hi:[1,0]
	v_pk_mul_f32 v[34:35], v[34:35], v[74:75] op_sel_hi:[1,0]
	v_pk_mul_f32 v[32:33], v[32:33], v[74:75] op_sel_hi:[1,0]
	v_pk_mul_f32 v[30:31], v[30:31], v[74:75] op_sel_hi:[1,0]
	v_pk_mul_f32 v[28:29], v[28:29], v[74:75] op_sel_hi:[1,0]
	v_pk_mul_f32 v[26:27], v[26:27], v[74:75] op_sel_hi:[1,0]
	v_pk_mul_f32 v[24:25], v[24:25], v[74:75] op_sel_hi:[1,0]
	v_pk_mul_f32 v[22:23], v[22:23], v[74:75] op_sel_hi:[1,0]
	v_pk_mul_f32 v[20:21], v[20:21], v[74:75] op_sel_hi:[1,0]
	v_pk_mul_f32 v[18:19], v[18:19], v[74:75] op_sel_hi:[1,0]
	v_pk_mul_f32 v[16:17], v[16:17], v[74:75] op_sel_hi:[1,0]
	v_mul_f32_e32 v64, v64, v74

; __device__ __forceinline__ unsigned cvt_pk_bf16(float lo, float hi) { unsigned r; asm volatile("v_cvt_pk_bf16_f32 %0, %1, %2" : "=v"(r) : "v"(lo), "v"(hi)); return r; }
; __device__ __forceinline__ void attn_passes(const Params& p, LAS unsigned char* lds) {
;     ...
;             float lt = lsum; lt += __shfl_xor(lt, 16); lt += __shfl_xor(lt, 32);
; #pragma unroll
;             for (int c = 0; c < 8; c += 2) {
;                 unsigned ax = cvt_pk_bf16(o[c][0], o[c][1]), ay = cvt_pk_bf16(o[c][2], o[c][3]), bx = cvt_pk_bf16(o[c + 1][0], o[c + 1][1]), by = cvt_pk_bf16(o[c + 1][2], o[c + 1][3]);
;                 const auto rx = __builtin_amdgcn_permlane16_swap(ax, bx, false, false); const auto ry = __builtin_amdgcn_permlane16_swap(ay, by, false, false);
;                 u32x4 sw; sw.x = rx[0]; sw.y = ry[0]; sw.z = rx[1]; sw.w = ry[1];
;                 *(u32x4*)(ob_bh + tq * 2048 + 16 * (c + (g & 1)) + 8 * (g >> 1)) = sw; }
;             if (g == 0) { ml_bh[tq * 32] = m; ml_bh[tq * 32 + 1] = lt; }
.LBB0_314:
	s_nop 1
	v_add_f32_e32 v16, 0, v65
	v_add_f32_e32 v16, v66, v16
	v_add_f32_e32 v16, v67, v16
	v_add_f32_e32 v16, v68, v16
	v_add_f32_e32 v16, v69, v16
	v_add_f32_e32 v16, v70, v16
	v_add_f32_e32 v16, v71, v16
	v_add_f32_e32 v16, v72, v16
	v_add_f32_e32 v18, v64, v16
	v_mov_b32_e32 v19, v18
	v_lshlrev_b64 v[16:17], s87, v[90:91]
	v_lshl_add_u64 v[16:17], v[16:17], 0, s[22:23]
	s_barrier
	v_lshlrev_b64 v[24:25], 12, v[16:17]
	v_cvt_pk_bf16_f32 v20, v44, v45
	v_cvt_pk_bf16_f32 v21, v46, v47
	v_cvt_pk_bf16_f32 v22, v40, v41
	v_cvt_pk_bf16_f32 v23, v42, v43
	v_lshl_add_u64 v[24:25], v[156:157], 0, v[24:25]
	v_permlane16_swap_b32_e32 v20, v22
	v_permlane16_swap_b32_e32 v21, v23
	v_permlane16_swap_b32_e32 v18, v19
	v_add_f32_e32 v18, v18, v19
	global_store_dwordx4 v[24:25], v[20:23], off
	v_mov_b32_e32 v19, v18
	v_mov_b32_e32 v161, v18
	s_nop 0
	v_cvt_pk_bf16_f32 v20, v36, v37
	v_cvt_pk_bf16_f32 v21, v38, v39
	v_cvt_pk_bf16_f32 v22, v32, v33
	v_cvt_pk_bf16_f32 v23, v34, v35
	s_nop 0
	v_permlane16_swap_b32_e32 v20, v22
	v_permlane16_swap_b32_e32 v21, v23
	global_store_dwordx4 v[24:25], v[20:23], off offset:64
	v_cvt_pk_bf16_f32 v12, v12, v13
	v_cvt_pk_bf16_f32 v13, v14, v15
	v_cvt_pk_bf16_f32 v14, v8, v9
	v_cvt_pk_bf16_f32 v15, v10, v11
	s_nop 0
	v_permlane16_swap_b32_e32 v12, v14
	v_permlane16_swap_b32_e32 v13, v15
	global_store_dwordx4 v[24:25], v[12:15], off offset:128
	v_cvt_pk_bf16_f32 v4, v4, v5
	v_cvt_pk_bf16_f32 v5, v6, v7
	v_cvt_pk_bf16_f32 v6, v0, v1
	v_cvt_pk_bf16_f32 v7, v2, v3
	s_nop 0
	v_permlane16_swap_b32_e32 v4, v6
	v_permlane16_swap_b32_e32 v5, v7
	global_store_dwordx4 v[24:25], v[4:7], off offset:192
	v_permlane32_swap_b32_e32 v161, v19
	s_and_saveexec_b64 s[6:7], s[4:5]
	s_cbranch_execz .LBB0_256
	v_lshlrev_b64 v[0:1], 7, v[16:17]
	v_lshl_add_u64 v[0:1], s[48:49], 0, v[0:1]
	s_waitcnt lgkmcnt(0)
	v_add_f32_e32 v161, v18, v19
	global_store_dwordx2 v[0:1], v[160:161], off
	s_branch .LBB0_256

; __device__ __forceinline__ void p3_pool(const Params& p) {
;     const bf16_t* proj = (const bf16_t*)(p.ws + WS_PROJ2); bf16_t* ycat = (bf16_t*)(p.ws + WS_YCAT);
;     const int tid = threadIdx.x, cch = tid & 255, sub = tid >> 8, j0 = cch * 8;
;     const int w = 2 << (j0 >> 9);
;     float ps[8];
;     { const f32x4 a = *(const f32x4*)(p.pool_scale + j0), b = *(const f32x4*)(p.pool_scale + j0 + 4); ps[0] = a[0]; ps[1] = a[1]; ps[2] = a[2]; ps[3] = a[3]; ps[4] = b[0]; ps[5] = b[1]; ps[6] = b[2]; ps[7] = b[3]; }
;     for (int item = blockIdx.x; item < 256; item += gridDim.x) {
;         const int t0 = item * 64 + sub * 32, pos0 = t0 & (SEQ - 1);
; __global__ void __launch_bounds__(NTHREADS, 2) fwd_megakernel(Params p) {
;     ...
;     p3_pool(p);
.LBB0_318:
	s_or_b64 exec, exec, s[4:5]
	v_and_b32_e32 v34, 0x7f8, v172
	s_and_b64 vcc, exec, s[0:1]
	v_mov_b32_e32 v9, 0
	s_cbranch_vccnz .LBB0_335
	s_bitcmp1_b32 s2, 0
	s_cbranch_scc1 .LBB0_335
	v_lshlrev_b32_e32 v8, 2, v34
	global_load_dwordx4 v[0:3], v8, s[30:31]
	global_load_dwordx4 v[4:7], v8, s[30:31] offset:16
	v_lshrrev_b32_e32 v24, 9, v34
	v_lshlrev_b32_e32 v16, 1, v34
	v_readfirstlane_b32 s100, v24
	v_readfirstlane_b32 s96, v173
	v_add_u32_e32 v17, 0x2000, v16
	v_add_u32_e32 v16, 0x1000, v16
	v_sub_u32_e32 v19, 126, v24
	v_lshlrev_b32_e32 v19, 23, v19
	s_nop 3
	s_lshl_b32 s100, 2, s100
	s_add_i32 s11, s100, -1
	s_mul_i32 s22, s11, 0x3000
	s_mov_b32 s12, s2
	s_waitcnt vmcnt(0)

; __global__ void __launch_bounds__(NTHREADS, 2) fwd_megakernel(Params p) {
	.amdhsa_kernel _Z14fwd_megakernel6Params
		.amdhsa_group_segment_fixed_size 0
		.amdhsa_private_segment_fixed_size 0
		.amdhsa_kernarg_size 352
		.amdhsa_user_sgpr_count 2
		.amdhsa_user_sgpr_dispatch_ptr 0
		.amdhsa_user_sgpr_queue_ptr 0
		.amdhsa_user_sgpr_kernarg_segment_ptr 1
		.amdhsa_user_sgpr_dispatch_id 0
		.amdhsa_user_sgpr_kernarg_preload_length 0
		.amdhsa_user_sgpr_kernarg_preload_offset 0
		.amdhsa_user_sgpr_private_segment_size 0
		.amdhsa_uses_dynamic_stack 0
		.amdhsa_enable_private_segment 0
		.amdhsa_system_sgpr_workgroup_id_x 1
		.amdhsa_system_sgpr_workgroup_id_y 0
		.amdhsa_system_sgpr_workgroup_id_z 0
		.amdhsa_system_sgpr_workgroup_info 0
		.amdhsa_system_vgpr_workitem_id 2
		.amdhsa_next_free_vgpr 240
		.amdhsa_next_free_sgpr 102
		.amdhsa_accum_offset 240
		.amdhsa_reserve_vcc 1
		.amdhsa_float_round_mode_32 0
		.amdhsa_float_round_mode_16_64 0
		.amdhsa_float_denorm_mode_32 3
		.amdhsa_float_denorm_mode_16_64 3
		.amdhsa_dx10_clamp 1
		.amdhsa_ieee_mode 1
		.amdhsa_fp16_overflow 0
		.amdhsa_tg_split 0
		.amdhsa_exception_fp_ieee_invalid_op 0
		.amdhsa_exception_fp_denorm_src 0
		.amdhsa_exception_fp_ieee_div_zero 0
		.amdhsa_exception_fp_ieee_overflow 0
		.amdhsa_exception_fp_ieee_underflow 0
		.amdhsa_exception_fp_ieee_inexact 0
		.amdhsa_exception_int_div_zero 0
	.end_amdhsa_kernel

; __global__ void __launch_bounds__(NTHREADS, 2) fwd_megakernel(Params p) {
amdhsa.kernels:
  - .agpr_count:     0
    .args:
      - .offset:         0
        .size:           96
        .value_kind:     by_value
      - .offset:         96
        .size:           4
        .value_kind:     hidden_block_count_x
      - .offset:         100
        .size:           4
        .value_kind:     hidden_block_count_y
      - .offset:         104
        .size:           4
        .value_kind:     hidden_block_count_z
      - .offset:         108
        .size:           2
        .value_kind:     hidden_group_size_x
      - .offset:         110
        .size:           2
        .value_kind:     hidden_group_size_y
      - .offset:         112
        .size:           2
        .value_kind:     hidden_group_size_z
      - .offset:         114
        .size:           2
        .value_kind:     hidden_remainder_x
      - .offset:         116
        .size:           2
        .value_kind:     hidden_remainder_y
      - .offset:         118
        .size:           2
        .value_kind:     hidden_remainder_z
      - .offset:         136
        .size:           8
        .value_kind:     hidden_global_offset_x
      - .offset:         144
        .size:           8
        .value_kind:     hidden_global_offset_y
      - .offset:         152
        .size:           8
        .value_kind:     hidden_global_offset_z
      - .offset:         160
        .size:           2
        .value_kind:     hidden_grid_dims
      - .offset:         184
        .size:           8
        .value_kind:     hidden_multigrid_sync_arg
      - .offset:         216
        .size:           4
        .value_kind:     hidden_dynamic_lds_size
    .group_segment_fixed_size: 0
    .kernarg_segment_align: 8
    .kernarg_segment_size: 352
    .language:       OpenCL C
    .language_version:
      - 2
      - 0
    .max_flat_workgroup_size: 512
    .name:           _Z14fwd_megakernel6Params
    .private_segment_fixed_size: 0
    .sgpr_count:     108
    .sgpr_spill_count: 0
    .symbol:         _Z14fwd_megakernel6Params.kd
    .uniform_work_group_size: 1
    .uses_dynamic_stack: false
    .vgpr_count:     240
    .vgpr_spill_count: 0
    .wavefront_size: 64
